# global seams: non-leader workgroups wait on the cross-XCD release word directly (constant generation per seam) instead of the per-XCD re-publish
# speedup vs baseline: 1.0082x; 1.0082x over previous
.Lxb0_276:
	s_or_b64 exec, exec, s[10:11]
	v_cvt_f32_u32_e32 v4, v2
	s_waitcnt vmcnt(0)
	v_readfirstlane_b32 s0, v3
	v_sub_u32_e32 v3, 0, v2
	v_rcp_iflag_f32_e32 v4, v4
	v_add_u32_e32 v5, s0, v1
	v_mul_f32_e32 v4, 0x4f7ffffe, v4
	v_cvt_u32_f32_e32 v4, v4
	v_mul_lo_u32 v1, v3, v4
	v_mul_hi_u32 v1, v4, v1
	v_add_u32_e32 v1, v4, v1
	v_mul_hi_u32 v1, v5, v1
	v_mul_lo_u32 v3, v1, v2
	v_sub_u32_e32 v3, v5, v3
	v_add_u32_e32 v4, 1, v1
	v_cmp_ge_u32_e32 vcc, v3, v2
	s_nop 1
	v_cndmask_b32_e32 v1, v1, v4, vcc
	v_sub_u32_e32 v4, v3, v2
	v_cndmask_b32_e32 v3, v3, v4, vcc
	v_add_u32_e32 v4, 1, v1
	v_cmp_ge_u32_e32 vcc, v3, v2
	v_add_u32_e32 v3, 1, v5
	s_nop 0
	v_cndmask_b32_e32 v1, v1, v4, vcc
	v_mul_lo_u32 v4, v2, v1
	v_add_u32_e32 v2, v4, v2
	v_cmp_ne_u32_e32 vcc, v3, v2
	s_and_saveexec_b64 s[0:1], vcc
	s_xor_b64 s[8:9], exec, s[0:1]
	s_cbranch_execz .Lxb0_290
	s_waitcnt lgkmcnt(0)
	v_mov_b32_e32 v1, 0
	v_mov_b32_e32 v0, 0x3500
	global_load_dword v0, v0, s[40:41] sc1
	s_add_u32 s12, s40, 0x3500
	s_addc_u32 s13, s41, 0
	s_waitcnt vmcnt(0)
	v_cmp_eq_u32_e32 vcc, v0, v1
	s_and_saveexec_b64 s[10:11], vcc
	s_cbranch_execz .Lxb0_289
	s_mov_b32 s0, 1
	s_mov_b64 s[14:15], 0
	v_mov_b32_e32 v0, 0
	s_branch .Lxb0_280

.LBB0_454:
	s_or_b64 exec, exec, s[10:11]
	v_cvt_f32_u32_e32 v4, v2
	s_waitcnt vmcnt(0)
	v_readfirstlane_b32 s0, v3
	v_sub_u32_e32 v3, 0, v2
	v_rcp_iflag_f32_e32 v4, v4
	v_add_u32_e32 v5, s0, v1
	v_mul_f32_e32 v4, 0x4f7ffffe, v4
	v_cvt_u32_f32_e32 v4, v4
	v_mul_lo_u32 v1, v3, v4
	v_mul_hi_u32 v1, v4, v1
	v_add_u32_e32 v1, v4, v1
	v_mul_hi_u32 v1, v5, v1
	v_mul_lo_u32 v3, v1, v2
	v_sub_u32_e32 v3, v5, v3
	v_add_u32_e32 v4, 1, v1
	v_cmp_ge_u32_e32 vcc, v3, v2
	s_nop 1
	v_cndmask_b32_e32 v1, v1, v4, vcc
	v_sub_u32_e32 v4, v3, v2
	v_cndmask_b32_e32 v3, v3, v4, vcc
	v_add_u32_e32 v4, 1, v1
	v_cmp_ge_u32_e32 vcc, v3, v2
	v_add_u32_e32 v3, 1, v5
	s_nop 0
	v_cndmask_b32_e32 v1, v1, v4, vcc
	v_mul_lo_u32 v4, v2, v1
	v_add_u32_e32 v2, v4, v2
	v_cmp_ne_u32_e32 vcc, v3, v2
	s_and_saveexec_b64 s[0:1], vcc
	s_xor_b64 s[8:9], exec, s[0:1]
	s_cbranch_execz .LBB0_468
	s_waitcnt lgkmcnt(0)
	v_mov_b32_e32 v1, 1
	v_mov_b32_e32 v0, 0x3500
	global_load_dword v0, v0, s[40:41] sc1
	s_add_u32 s12, s40, 0x3500
	s_addc_u32 s13, s41, 0
	s_waitcnt vmcnt(0)
	v_cmp_eq_u32_e32 vcc, v0, v1
	s_and_saveexec_b64 s[10:11], vcc
	s_cbranch_execz .LBB0_467
	s_mov_b32 s0, 1
	s_mov_b64 s[14:15], 0
	v_mov_b32_e32 v0, 0
	s_branch .LBB0_458

.LBB0_665:
	s_or_b64 exec, exec, s[10:11]
	v_cvt_f32_u32_e32 v4, v2
	s_waitcnt vmcnt(0)
	v_readfirstlane_b32 s0, v3
	v_sub_u32_e32 v3, 0, v2
	v_rcp_iflag_f32_e32 v4, v4
	v_add_u32_e32 v5, s0, v1
	v_mul_f32_e32 v4, 0x4f7ffffe, v4
	v_cvt_u32_f32_e32 v4, v4
	v_mul_lo_u32 v1, v3, v4
	v_mul_hi_u32 v1, v4, v1
	v_add_u32_e32 v1, v4, v1
	v_mul_hi_u32 v1, v5, v1
	v_mul_lo_u32 v3, v1, v2
	v_sub_u32_e32 v3, v5, v3
	v_add_u32_e32 v4, 1, v1
	v_cmp_ge_u32_e32 vcc, v3, v2
	s_nop 1
	v_cndmask_b32_e32 v1, v1, v4, vcc
	v_sub_u32_e32 v4, v3, v2
	v_cndmask_b32_e32 v3, v3, v4, vcc
	v_add_u32_e32 v4, 1, v1
	v_cmp_ge_u32_e32 vcc, v3, v2
	v_add_u32_e32 v3, 1, v5
	s_nop 0
	v_cndmask_b32_e32 v1, v1, v4, vcc
	v_mul_lo_u32 v4, v2, v1
	v_add_u32_e32 v2, v4, v2
	v_cmp_ne_u32_e32 vcc, v3, v2
	s_and_saveexec_b64 s[0:1], vcc
	s_xor_b64 s[8:9], exec, s[0:1]
	s_cbranch_execz .LBB0_679
	s_waitcnt lgkmcnt(0)
	v_mov_b32_e32 v1, 2
	v_mov_b32_e32 v0, 0x3500
	global_load_dword v0, v0, s[40:41] sc1
	s_add_u32 s12, s40, 0x3500
	s_addc_u32 s13, s41, 0
	s_waitcnt vmcnt(0)
	v_cmp_eq_u32_e32 vcc, v0, v1
	s_and_saveexec_b64 s[10:11], vcc
	s_cbranch_execz .LBB0_678
	s_mov_b32 s0, 1
	s_mov_b64 s[14:15], 0
	v_mov_b32_e32 v0, 0
	s_branch .LBB0_669

.LBB0_832:
	s_or_b64 exec, exec, s[12:13]
	v_cvt_f32_u32_e32 v4, v2
	s_waitcnt vmcnt(0)
	v_readfirstlane_b32 s0, v3
	v_sub_u32_e32 v3, 0, v2
	v_rcp_iflag_f32_e32 v4, v4
	v_add_u32_e32 v5, s0, v1
	v_mul_f32_e32 v4, 0x4f7ffffe, v4
	v_cvt_u32_f32_e32 v4, v4
	v_mul_lo_u32 v1, v3, v4
	v_mul_hi_u32 v1, v4, v1
	v_add_u32_e32 v1, v4, v1
	v_mul_hi_u32 v1, v5, v1
	v_mul_lo_u32 v3, v1, v2
	v_sub_u32_e32 v3, v5, v3
	v_add_u32_e32 v4, 1, v1
	v_cmp_ge_u32_e32 vcc, v3, v2
	s_nop 1
	v_cndmask_b32_e32 v1, v1, v4, vcc
	v_sub_u32_e32 v4, v3, v2
	v_cndmask_b32_e32 v3, v3, v4, vcc
	v_add_u32_e32 v4, 1, v1
	v_cmp_ge_u32_e32 vcc, v3, v2
	v_add_u32_e32 v3, 1, v5
	s_nop 0
	v_cndmask_b32_e32 v1, v1, v4, vcc
	v_mul_lo_u32 v4, v2, v1
	v_add_u32_e32 v2, v4, v2
	v_cmp_ne_u32_e32 vcc, v3, v2
	s_and_saveexec_b64 s[0:1], vcc
	s_xor_b64 s[10:11], exec, s[0:1]
	s_cbranch_execz .LBB0_846
	s_waitcnt lgkmcnt(0)
	v_mov_b32_e32 v1, 3
	v_mov_b32_e32 v0, 0x3500
	global_load_dword v0, v0, s[40:41] sc1
	s_add_u32 s14, s40, 0x3500
	s_addc_u32 s15, s41, 0
	s_waitcnt vmcnt(0)
	v_cmp_eq_u32_e32 vcc, v0, v1
	s_and_saveexec_b64 s[12:13], vcc
	s_cbranch_execz .LBB0_845
	s_mov_b32 s0, 1
	s_mov_b64 s[16:17], 0
	v_mov_b32_e32 v0, 0
	s_branch .LBB0_836

.LBB0_963:
	s_or_b64 exec, exec, s[12:13]
	v_cvt_f32_u32_e32 v4, v2
	s_waitcnt vmcnt(0)
	v_readfirstlane_b32 s2, v3
	v_sub_u32_e32 v3, 0, v2
	v_rcp_iflag_f32_e32 v4, v4
	v_add_u32_e32 v5, s2, v1
	v_mul_f32_e32 v4, 0x4f7ffffe, v4
	v_cvt_u32_f32_e32 v4, v4
	v_mul_lo_u32 v1, v3, v4
	v_mul_hi_u32 v1, v4, v1
	v_add_u32_e32 v1, v4, v1
	v_mul_hi_u32 v1, v5, v1
	v_mul_lo_u32 v3, v1, v2
	v_sub_u32_e32 v3, v5, v3
	v_add_u32_e32 v4, 1, v1
	v_cmp_ge_u32_e32 vcc, v3, v2
	s_nop 1
	v_cndmask_b32_e32 v1, v1, v4, vcc
	v_sub_u32_e32 v4, v3, v2
	v_cndmask_b32_e32 v3, v3, v4, vcc
	v_add_u32_e32 v4, 1, v1
	v_cmp_ge_u32_e32 vcc, v3, v2
	v_add_u32_e32 v3, 1, v5
	s_nop 0
	v_cndmask_b32_e32 v1, v1, v4, vcc
	v_mul_lo_u32 v4, v2, v1
	v_add_u32_e32 v2, v4, v2
	v_cmp_ne_u32_e32 vcc, v3, v2
	s_and_saveexec_b64 s[2:3], vcc
	s_xor_b64 s[10:11], exec, s[2:3]
	s_cbranch_execz .LBB0_977
	s_waitcnt lgkmcnt(0)
	v_mov_b32_e32 v1, 4
	v_mov_b32_e32 v0, 0x3500
	global_load_dword v0, v0, s[40:41] sc1
	s_add_u32 s14, s40, 0x3500
	s_addc_u32 s15, s41, 0
	s_waitcnt vmcnt(0)
	v_cmp_eq_u32_e32 vcc, v0, v1
	s_and_saveexec_b64 s[12:13], vcc
	s_cbranch_execz .LBB0_976
	s_mov_b32 s2, 1
	s_mov_b64 s[16:17], 0
	v_mov_b32_e32 v0, 0
	s_branch .LBB0_967

.LBB0_1088:
	s_or_b64 exec, exec, s[10:11]
	v_cvt_f32_u32_e32 v4, v2
	s_waitcnt vmcnt(0)
	v_readfirstlane_b32 s0, v3
	v_sub_u32_e32 v3, 0, v2
	v_rcp_iflag_f32_e32 v4, v4
	v_add_u32_e32 v5, s0, v1
	v_mul_f32_e32 v4, 0x4f7ffffe, v4
	v_cvt_u32_f32_e32 v4, v4
	v_mul_lo_u32 v1, v3, v4
	v_mul_hi_u32 v1, v4, v1
	v_add_u32_e32 v1, v4, v1
	v_mul_hi_u32 v1, v5, v1
	v_mul_lo_u32 v3, v1, v2
	v_sub_u32_e32 v3, v5, v3
	v_add_u32_e32 v4, 1, v1
	v_cmp_ge_u32_e32 vcc, v3, v2
	s_nop 1
	v_cndmask_b32_e32 v1, v1, v4, vcc
	v_sub_u32_e32 v4, v3, v2
	v_cndmask_b32_e32 v3, v3, v4, vcc
	v_add_u32_e32 v4, 1, v1
	v_cmp_ge_u32_e32 vcc, v3, v2
	v_add_u32_e32 v3, 1, v5
	s_nop 0
	v_cndmask_b32_e32 v1, v1, v4, vcc
	v_mul_lo_u32 v4, v2, v1
	v_add_u32_e32 v2, v4, v2
	v_cmp_ne_u32_e32 vcc, v3, v2
	s_and_saveexec_b64 s[0:1], vcc
	s_xor_b64 s[8:9], exec, s[0:1]
	s_cbranch_execz .LBB0_1102
	s_waitcnt lgkmcnt(0)
	v_mov_b32_e32 v1, 5
	v_mov_b32_e32 v0, 0x3500
	global_load_dword v0, v0, s[40:41] sc1
	s_add_u32 s12, s40, 0x3500
	s_addc_u32 s13, s41, 0
	s_waitcnt vmcnt(0)
	v_cmp_eq_u32_e32 vcc, v0, v1
	s_and_saveexec_b64 s[10:11], vcc
	s_cbranch_execz .LBB0_1101
	s_mov_b32 s0, 1
	s_mov_b64 s[14:15], 0
	v_mov_b32_e32 v0, 0
	s_branch .LBB0_1092

.LBB0_1168:
	s_or_b64 exec, exec, s[10:11]
	v_cvt_f32_u32_e32 v4, v2
	s_waitcnt vmcnt(0)
	v_readfirstlane_b32 s0, v3
	v_sub_u32_e32 v3, 0, v2
	v_rcp_iflag_f32_e32 v4, v4
	v_add_u32_e32 v5, s0, v1
	v_mul_f32_e32 v4, 0x4f7ffffe, v4
	v_cvt_u32_f32_e32 v4, v4
	v_mul_lo_u32 v1, v3, v4
	v_mul_hi_u32 v1, v4, v1
	v_add_u32_e32 v1, v4, v1
	v_mul_hi_u32 v1, v5, v1
	v_mul_lo_u32 v3, v1, v2
	v_sub_u32_e32 v3, v5, v3
	v_add_u32_e32 v4, 1, v1
	v_cmp_ge_u32_e32 vcc, v3, v2
	s_nop 1
	v_cndmask_b32_e32 v1, v1, v4, vcc
	v_sub_u32_e32 v4, v3, v2
	v_cndmask_b32_e32 v3, v3, v4, vcc
	v_add_u32_e32 v4, 1, v1
	v_cmp_ge_u32_e32 vcc, v3, v2
	v_add_u32_e32 v3, 1, v5
	s_nop 0
	v_cndmask_b32_e32 v1, v1, v4, vcc
	v_mul_lo_u32 v4, v2, v1
	v_add_u32_e32 v2, v4, v2
	v_cmp_ne_u32_e32 vcc, v3, v2
	s_and_saveexec_b64 s[0:1], vcc
	s_xor_b64 s[8:9], exec, s[0:1]
	s_cbranch_execz .LBB0_1182
	s_waitcnt lgkmcnt(0)
	v_mov_b32_e32 v1, 6
	v_mov_b32_e32 v0, 0x3500
	global_load_dword v0, v0, s[40:41] sc1
	s_add_u32 s12, s40, 0x3500
	s_addc_u32 s13, s41, 0
	s_waitcnt vmcnt(0)
	v_cmp_eq_u32_e32 vcc, v0, v1
	s_and_saveexec_b64 s[10:11], vcc
	s_cbranch_execz .LBB0_1181
	s_mov_b32 s0, 1
	s_mov_b64 s[14:15], 0
	v_mov_b32_e32 v0, 0
	s_branch .LBB0_1172

.LBB0_1661:
	s_or_b64 exec, exec, s[10:11]
	v_cvt_f32_u32_e32 v4, v2
	s_waitcnt vmcnt(0)
	v_readfirstlane_b32 s0, v3
	v_sub_u32_e32 v3, 0, v2
	v_rcp_iflag_f32_e32 v4, v4
	v_add_u32_e32 v5, s0, v1
	v_mul_f32_e32 v4, 0x4f7ffffe, v4
	v_cvt_u32_f32_e32 v4, v4
	v_mul_lo_u32 v1, v3, v4
	v_mul_hi_u32 v1, v4, v1
	v_add_u32_e32 v1, v4, v1
	v_mul_hi_u32 v1, v5, v1
	v_mul_lo_u32 v3, v1, v2
	v_sub_u32_e32 v3, v5, v3
	v_add_u32_e32 v4, 1, v1
	v_cmp_ge_u32_e32 vcc, v3, v2
	s_nop 1
	v_cndmask_b32_e32 v1, v1, v4, vcc
	v_sub_u32_e32 v4, v3, v2
	v_cndmask_b32_e32 v3, v3, v4, vcc
	v_add_u32_e32 v4, 1, v1
	v_cmp_ge_u32_e32 vcc, v3, v2
	v_add_u32_e32 v3, 1, v5
	s_nop 0
	v_cndmask_b32_e32 v1, v1, v4, vcc
	v_mul_lo_u32 v4, v2, v1
	v_add_u32_e32 v2, v4, v2
	v_cmp_ne_u32_e32 vcc, v3, v2
	s_and_saveexec_b64 s[0:1], vcc
	s_xor_b64 s[8:9], exec, s[0:1]
	s_cbranch_execz .LBB0_1675
	s_waitcnt lgkmcnt(0)
	v_mov_b32_e32 v1, 7
	v_mov_b32_e32 v0, 0x3500
	global_load_dword v0, v0, s[40:41] sc1
	s_add_u32 s12, s40, 0x3500
	s_addc_u32 s13, s41, 0
	s_waitcnt vmcnt(0)
	v_cmp_eq_u32_e32 vcc, v0, v1
	s_and_saveexec_b64 s[10:11], vcc
	s_cbranch_execz .LBB0_1674
	s_mov_b32 s0, 1
	s_mov_b64 s[14:15], 0
	v_mov_b32_e32 v0, 0
	s_branch .LBB0_1665

.LBB0_1914:
	s_or_b64 exec, exec, s[10:11]
	v_cvt_f32_u32_e32 v4, v2
	s_waitcnt vmcnt(0)
	v_readfirstlane_b32 s0, v3
	v_sub_u32_e32 v3, 0, v2
	v_rcp_iflag_f32_e32 v4, v4
	v_add_u32_e32 v5, s0, v1
	v_mul_f32_e32 v4, 0x4f7ffffe, v4
	v_cvt_u32_f32_e32 v4, v4
	v_mul_lo_u32 v1, v3, v4
	v_mul_hi_u32 v1, v4, v1
	v_add_u32_e32 v1, v4, v1
	v_mul_hi_u32 v1, v5, v1
	v_mul_lo_u32 v3, v1, v2
	v_sub_u32_e32 v3, v5, v3
	v_add_u32_e32 v4, 1, v1
	v_cmp_ge_u32_e32 vcc, v3, v2
	s_nop 1
	v_cndmask_b32_e32 v1, v1, v4, vcc
	v_sub_u32_e32 v4, v3, v2
	v_cndmask_b32_e32 v3, v3, v4, vcc
	v_add_u32_e32 v4, 1, v1
	v_cmp_ge_u32_e32 vcc, v3, v2
	v_add_u32_e32 v3, 1, v5
	s_nop 0
	v_cndmask_b32_e32 v1, v1, v4, vcc
	v_mul_lo_u32 v4, v2, v1
	v_add_u32_e32 v2, v4, v2
	v_cmp_ne_u32_e32 vcc, v3, v2
	s_and_saveexec_b64 s[0:1], vcc
	s_xor_b64 s[8:9], exec, s[0:1]
	s_cbranch_execz .LBB0_1928
	s_waitcnt lgkmcnt(0)
	v_mov_b32_e32 v1, 8
	v_mov_b32_e32 v0, 0x3500
	global_load_dword v0, v0, s[40:41] sc1
	s_add_u32 s12, s40, 0x3500
	s_addc_u32 s13, s41, 0
	s_waitcnt vmcnt(0)
	v_cmp_eq_u32_e32 vcc, v0, v1
	s_and_saveexec_b64 s[10:11], vcc
	s_cbranch_execz .LBB0_1927
	s_mov_b32 s0, 1
	s_mov_b64 s[14:15], 0
	v_mov_b32_e32 v0, 0
	s_branch .LBB0_1918

.LBB0_2163:
	s_or_b64 exec, exec, s[10:11]
	v_cvt_f32_u32_e32 v4, v2
	s_waitcnt vmcnt(0)
	v_readfirstlane_b32 s0, v3
	v_sub_u32_e32 v3, 0, v2
	v_rcp_iflag_f32_e32 v4, v4
	v_add_u32_e32 v5, s0, v1
	v_mul_f32_e32 v4, 0x4f7ffffe, v4
	v_cvt_u32_f32_e32 v4, v4
	v_mul_lo_u32 v1, v3, v4
	v_mul_hi_u32 v1, v4, v1
	v_add_u32_e32 v1, v4, v1
	v_mul_hi_u32 v1, v5, v1
	v_mul_lo_u32 v3, v1, v2
	v_sub_u32_e32 v3, v5, v3
	v_add_u32_e32 v4, 1, v1
	v_cmp_ge_u32_e32 vcc, v3, v2
	s_nop 1
	v_cndmask_b32_e32 v1, v1, v4, vcc
	v_sub_u32_e32 v4, v3, v2
	v_cndmask_b32_e32 v3, v3, v4, vcc
	v_add_u32_e32 v4, 1, v1
	v_cmp_ge_u32_e32 vcc, v3, v2
	v_add_u32_e32 v3, 1, v5
	s_nop 0
	v_cndmask_b32_e32 v1, v1, v4, vcc
	v_mul_lo_u32 v4, v2, v1
	v_add_u32_e32 v2, v4, v2
	v_cmp_ne_u32_e32 vcc, v3, v2
	s_and_saveexec_b64 s[0:1], vcc
	s_xor_b64 s[8:9], exec, s[0:1]
	s_cbranch_execz .LBB0_2177
	s_waitcnt lgkmcnt(0)
	v_mov_b32_e32 v1, 9
	v_mov_b32_e32 v0, 0x3500
	global_load_dword v0, v0, s[40:41] sc1
	s_add_u32 s12, s40, 0x3500
	s_addc_u32 s13, s41, 0
	s_waitcnt vmcnt(0)
	v_cmp_eq_u32_e32 vcc, v0, v1
	s_and_saveexec_b64 s[10:11], vcc
	s_cbranch_execz .LBB0_2176
	s_mov_b32 s0, 1
	s_mov_b64 s[14:15], 0
	v_mov_b32_e32 v0, 0
	s_branch .LBB0_2167

.LBB0_2374:
	s_or_b64 exec, exec, s[10:11]
	v_cvt_f32_u32_e32 v4, v2
	s_waitcnt vmcnt(0)
	v_readfirstlane_b32 s0, v3
	v_sub_u32_e32 v3, 0, v2
	v_rcp_iflag_f32_e32 v4, v4
	v_add_u32_e32 v5, s0, v1
	v_mul_f32_e32 v4, 0x4f7ffffe, v4
	v_cvt_u32_f32_e32 v4, v4
	v_mul_lo_u32 v1, v3, v4
	v_mul_hi_u32 v1, v4, v1
	v_add_u32_e32 v1, v4, v1
	v_mul_hi_u32 v1, v5, v1
	v_mul_lo_u32 v3, v1, v2
	v_sub_u32_e32 v3, v5, v3
	v_add_u32_e32 v4, 1, v1
	v_cmp_ge_u32_e32 vcc, v3, v2
	s_nop 1
	v_cndmask_b32_e32 v1, v1, v4, vcc
	v_sub_u32_e32 v4, v3, v2
	v_cndmask_b32_e32 v3, v3, v4, vcc
	v_add_u32_e32 v4, 1, v1
	v_cmp_ge_u32_e32 vcc, v3, v2
	v_add_u32_e32 v3, 1, v5
	s_nop 0
	v_cndmask_b32_e32 v1, v1, v4, vcc
	v_mul_lo_u32 v4, v2, v1
	v_add_u32_e32 v2, v4, v2
	v_cmp_ne_u32_e32 vcc, v3, v2
	s_and_saveexec_b64 s[0:1], vcc
	s_xor_b64 s[8:9], exec, s[0:1]
	s_cbranch_execz .LBB0_2388
	s_waitcnt lgkmcnt(0)
	v_mov_b32_e32 v1, 10
	v_mov_b32_e32 v0, 0x3500
	global_load_dword v0, v0, s[40:41] sc1
	s_add_u32 s12, s40, 0x3500
	s_addc_u32 s13, s41, 0
	s_waitcnt vmcnt(0)
	v_cmp_eq_u32_e32 vcc, v0, v1
	s_and_saveexec_b64 s[10:11], vcc
	s_cbranch_execz .LBB0_2387
	s_mov_b32 s0, 1
	s_mov_b64 s[14:15], 0
	v_mov_b32_e32 v0, 0
	s_branch .LBB0_2378

.LBB0_2541:
	s_or_b64 exec, exec, s[12:13]
	v_cvt_f32_u32_e32 v4, v2
	s_waitcnt vmcnt(0)
	v_readfirstlane_b32 s0, v3
	v_sub_u32_e32 v3, 0, v2
	v_rcp_iflag_f32_e32 v4, v4
	v_add_u32_e32 v5, s0, v1
	v_mul_f32_e32 v4, 0x4f7ffffe, v4
	v_cvt_u32_f32_e32 v4, v4
	v_mul_lo_u32 v1, v3, v4
	v_mul_hi_u32 v1, v4, v1
	v_add_u32_e32 v1, v4, v1
	v_mul_hi_u32 v1, v5, v1
	v_mul_lo_u32 v3, v1, v2
	v_sub_u32_e32 v3, v5, v3
	v_add_u32_e32 v4, 1, v1
	v_cmp_ge_u32_e32 vcc, v3, v2
	s_nop 1
	v_cndmask_b32_e32 v1, v1, v4, vcc
	v_sub_u32_e32 v4, v3, v2
	v_cndmask_b32_e32 v3, v3, v4, vcc
	v_add_u32_e32 v4, 1, v1
	v_cmp_ge_u32_e32 vcc, v3, v2
	v_add_u32_e32 v3, 1, v5
	s_nop 0
	v_cndmask_b32_e32 v1, v1, v4, vcc
	v_mul_lo_u32 v4, v2, v1
	v_add_u32_e32 v2, v4, v2
	v_cmp_ne_u32_e32 vcc, v3, v2
	s_and_saveexec_b64 s[0:1], vcc
	s_xor_b64 s[10:11], exec, s[0:1]
	s_cbranch_execz .LBB0_2555
	s_waitcnt lgkmcnt(0)
	v_mov_b32_e32 v1, 11
	v_mov_b32_e32 v0, 0x3500
	global_load_dword v0, v0, s[40:41] sc1
	s_add_u32 s14, s40, 0x3500
	s_addc_u32 s15, s41, 0
	s_waitcnt vmcnt(0)
	v_cmp_eq_u32_e32 vcc, v0, v1
	s_and_saveexec_b64 s[12:13], vcc
	s_cbranch_execz .LBB0_2554
	s_mov_b32 s0, 1
	s_mov_b64 s[16:17], 0
	v_mov_b32_e32 v0, 0
	s_branch .LBB0_2545

.LBB0_2669:
	s_or_b64 exec, exec, s[12:13]
	v_cvt_f32_u32_e32 v4, v2
	s_waitcnt vmcnt(0)
	v_readfirstlane_b32 s2, v3
	v_sub_u32_e32 v3, 0, v2
	v_rcp_iflag_f32_e32 v4, v4
	v_add_u32_e32 v5, s2, v1
	v_mul_f32_e32 v4, 0x4f7ffffe, v4
	v_cvt_u32_f32_e32 v4, v4
	v_mul_lo_u32 v1, v3, v4
	v_mul_hi_u32 v1, v4, v1
	v_add_u32_e32 v1, v4, v1
	v_mul_hi_u32 v1, v5, v1
	v_mul_lo_u32 v3, v1, v2
	v_sub_u32_e32 v3, v5, v3
	v_add_u32_e32 v4, 1, v1
	v_cmp_ge_u32_e32 vcc, v3, v2
	s_nop 1
	v_cndmask_b32_e32 v1, v1, v4, vcc
	v_sub_u32_e32 v4, v3, v2
	v_cndmask_b32_e32 v3, v3, v4, vcc
	v_add_u32_e32 v4, 1, v1
	v_cmp_ge_u32_e32 vcc, v3, v2
	v_add_u32_e32 v3, 1, v5
	s_nop 0
	v_cndmask_b32_e32 v1, v1, v4, vcc
	v_mul_lo_u32 v4, v2, v1
	v_add_u32_e32 v2, v4, v2
	v_cmp_ne_u32_e32 vcc, v3, v2
	s_and_saveexec_b64 s[2:3], vcc
	s_xor_b64 s[10:11], exec, s[2:3]
	s_cbranch_execz .LBB0_2683
	s_waitcnt lgkmcnt(0)
	v_mov_b32_e32 v1, 12
	v_mov_b32_e32 v0, 0x3500
	global_load_dword v0, v0, s[40:41] sc1
	s_add_u32 s14, s40, 0x3500
	s_addc_u32 s15, s41, 0
	s_waitcnt vmcnt(0)
	v_cmp_eq_u32_e32 vcc, v0, v1
	s_and_saveexec_b64 s[12:13], vcc
	s_cbranch_execz .LBB0_2682
	s_mov_b32 s2, 1
	s_mov_b64 s[16:17], 0
	v_mov_b32_e32 v0, 0
	s_branch .LBB0_2673

.LBB0_2794:
	s_or_b64 exec, exec, s[10:11]
	v_cvt_f32_u32_e32 v4, v2
	s_waitcnt vmcnt(0)
	v_readfirstlane_b32 s0, v3
	v_sub_u32_e32 v3, 0, v2
	v_rcp_iflag_f32_e32 v4, v4
	v_add_u32_e32 v5, s0, v1
	v_mul_f32_e32 v4, 0x4f7ffffe, v4
	v_cvt_u32_f32_e32 v4, v4
	v_mul_lo_u32 v1, v3, v4
	v_mul_hi_u32 v1, v4, v1
	v_add_u32_e32 v1, v4, v1
	v_mul_hi_u32 v1, v5, v1
	v_mul_lo_u32 v3, v1, v2
	v_sub_u32_e32 v3, v5, v3
	v_add_u32_e32 v4, 1, v1
	v_cmp_ge_u32_e32 vcc, v3, v2
	s_nop 1
	v_cndmask_b32_e32 v1, v1, v4, vcc
	v_sub_u32_e32 v4, v3, v2
	v_cndmask_b32_e32 v3, v3, v4, vcc
	v_add_u32_e32 v4, 1, v1
	v_cmp_ge_u32_e32 vcc, v3, v2
	v_add_u32_e32 v3, 1, v5
	s_nop 0
	v_cndmask_b32_e32 v1, v1, v4, vcc
	v_mul_lo_u32 v4, v2, v1
	v_add_u32_e32 v2, v4, v2
	v_cmp_ne_u32_e32 vcc, v3, v2
	s_and_saveexec_b64 s[0:1], vcc
	s_xor_b64 s[8:9], exec, s[0:1]
	s_cbranch_execz .LBB0_2808
	s_waitcnt lgkmcnt(0)
	v_mov_b32_e32 v1, 13
	v_mov_b32_e32 v0, 0x3500
	global_load_dword v0, v0, s[40:41] sc1
	s_add_u32 s12, s40, 0x3500
	s_addc_u32 s13, s41, 0
	s_waitcnt vmcnt(0)
	v_cmp_eq_u32_e32 vcc, v0, v1
	s_and_saveexec_b64 s[10:11], vcc
	s_cbranch_execz .LBB0_2807
	s_mov_b32 s0, 1
	s_mov_b64 s[14:15], 0
	v_mov_b32_e32 v0, 0
	s_branch .LBB0_2798

.LBB0_2874:
	s_or_b64 exec, exec, s[10:11]
	v_cvt_f32_u32_e32 v4, v2
	s_waitcnt vmcnt(0)
	v_readfirstlane_b32 s0, v3
	v_sub_u32_e32 v3, 0, v2
	v_rcp_iflag_f32_e32 v4, v4
	v_add_u32_e32 v5, s0, v1
	v_mul_f32_e32 v4, 0x4f7ffffe, v4
	v_cvt_u32_f32_e32 v4, v4
	v_mul_lo_u32 v1, v3, v4
	v_mul_hi_u32 v1, v4, v1
	v_add_u32_e32 v1, v4, v1
	v_mul_hi_u32 v1, v5, v1
	v_mul_lo_u32 v3, v1, v2
	v_sub_u32_e32 v3, v5, v3
	v_add_u32_e32 v4, 1, v1
	v_cmp_ge_u32_e32 vcc, v3, v2
	s_nop 1
	v_cndmask_b32_e32 v1, v1, v4, vcc
	v_sub_u32_e32 v4, v3, v2
	v_cndmask_b32_e32 v3, v3, v4, vcc
	v_add_u32_e32 v4, 1, v1
	v_cmp_ge_u32_e32 vcc, v3, v2
	v_add_u32_e32 v3, 1, v5
	s_nop 0
	v_cndmask_b32_e32 v1, v1, v4, vcc
	v_mul_lo_u32 v4, v2, v1
	v_add_u32_e32 v2, v4, v2
	v_cmp_ne_u32_e32 vcc, v3, v2
	s_and_saveexec_b64 s[0:1], vcc
	s_xor_b64 s[8:9], exec, s[0:1]
	s_cbranch_execz .LBB0_2888
	s_waitcnt lgkmcnt(0)
	v_mov_b32_e32 v1, 14
	v_mov_b32_e32 v0, 0x3500
	global_load_dword v0, v0, s[40:41] sc1
	s_add_u32 s12, s40, 0x3500
	s_addc_u32 s13, s41, 0
	s_waitcnt vmcnt(0)
	v_cmp_eq_u32_e32 vcc, v0, v1
	s_and_saveexec_b64 s[10:11], vcc
	s_cbranch_execz .LBB0_2887
	s_mov_b32 s0, 1
	s_mov_b64 s[14:15], 0
	v_mov_b32_e32 v0, 0
	s_branch .LBB0_2878

.LBB0_3367:
	s_or_b64 exec, exec, s[10:11]
	v_cvt_f32_u32_e32 v4, v2
	s_waitcnt vmcnt(0)
	v_readfirstlane_b32 s0, v3
	v_sub_u32_e32 v3, 0, v2
	v_rcp_iflag_f32_e32 v4, v4
	v_add_u32_e32 v5, s0, v1
	v_mul_f32_e32 v4, 0x4f7ffffe, v4
	v_cvt_u32_f32_e32 v4, v4
	v_mul_lo_u32 v1, v3, v4
	v_mul_hi_u32 v1, v4, v1
	v_add_u32_e32 v1, v4, v1
	v_mul_hi_u32 v1, v5, v1
	v_mul_lo_u32 v3, v1, v2
	v_sub_u32_e32 v3, v5, v3
	v_add_u32_e32 v4, 1, v1
	v_cmp_ge_u32_e32 vcc, v3, v2
	s_nop 1
	v_cndmask_b32_e32 v1, v1, v4, vcc
	v_sub_u32_e32 v4, v3, v2
	v_cndmask_b32_e32 v3, v3, v4, vcc
	v_add_u32_e32 v4, 1, v1
	v_cmp_ge_u32_e32 vcc, v3, v2
	v_add_u32_e32 v3, 1, v5
	s_nop 0
	v_cndmask_b32_e32 v1, v1, v4, vcc
	v_mul_lo_u32 v4, v2, v1
	v_add_u32_e32 v2, v4, v2
	v_cmp_ne_u32_e32 vcc, v3, v2
	s_and_saveexec_b64 s[0:1], vcc
	s_xor_b64 s[8:9], exec, s[0:1]
	s_cbranch_execz .LBB0_3381
	s_waitcnt lgkmcnt(0)
	v_mov_b32_e32 v1, 15
	v_mov_b32_e32 v0, 0x3500
	global_load_dword v0, v0, s[40:41] sc1
	s_add_u32 s12, s40, 0x3500
	s_addc_u32 s13, s41, 0
	s_waitcnt vmcnt(0)
	v_cmp_eq_u32_e32 vcc, v0, v1
	s_and_saveexec_b64 s[10:11], vcc
	s_cbranch_execz .LBB0_3380
	s_mov_b32 s0, 1
	s_mov_b64 s[14:15], 0
	v_mov_b32_e32 v0, 0
	s_branch .LBB0_3371

.LBB0_3425:
	s_or_b64 exec, exec, s[6:7]
	v_cvt_f32_u32_e32 v4, v2
	s_waitcnt vmcnt(0)
	v_readfirstlane_b32 s4, v3
	v_sub_u32_e32 v3, 0, v2
	v_rcp_iflag_f32_e32 v4, v4
	v_add_u32_e32 v5, s4, v1
	v_mul_f32_e32 v4, 0x4f7ffffe, v4
	v_cvt_u32_f32_e32 v4, v4
	v_mul_lo_u32 v1, v3, v4
	v_mul_hi_u32 v1, v4, v1
	v_add_u32_e32 v1, v4, v1
	v_mul_hi_u32 v1, v5, v1
	v_mul_lo_u32 v3, v1, v2
	v_sub_u32_e32 v3, v5, v3
	v_add_u32_e32 v4, 1, v1
	v_cmp_ge_u32_e32 vcc, v3, v2
	s_nop 1
	v_cndmask_b32_e32 v1, v1, v4, vcc
	v_sub_u32_e32 v4, v3, v2
	v_cndmask_b32_e32 v3, v3, v4, vcc
	v_add_u32_e32 v4, 1, v1
	v_cmp_ge_u32_e32 vcc, v3, v2
	v_add_u32_e32 v3, 1, v5
	s_nop 0
	v_cndmask_b32_e32 v1, v1, v4, vcc
	v_mul_lo_u32 v4, v2, v1
	v_add_u32_e32 v2, v4, v2
	v_cmp_ne_u32_e32 vcc, v3, v2
	s_and_saveexec_b64 s[4:5], vcc
	s_xor_b64 s[4:5], exec, s[4:5]
	s_cbranch_execz .LBB0_3439
	s_waitcnt lgkmcnt(0)
	v_mov_b32_e32 v1, 16
	v_mov_b32_e32 v0, 0x3500
	global_load_dword v0, v0, s[40:41] sc1
	s_add_u32 s8, s40, 0x3500
	s_addc_u32 s9, s41, 0
	s_waitcnt vmcnt(0)
	v_cmp_eq_u32_e32 vcc, v0, v1
	s_and_saveexec_b64 s[6:7], vcc
	s_cbranch_execz .LBB0_3438
	s_mov_b32 s20, 1
	s_mov_b64 s[10:11], 0
	v_mov_b32_e32 v0, 0
	s_branch .LBB0_3429
